# in-proj KN2 epilogue: xor16/xor32 all-reduce hops via v_permlane16_swap/v_permlane32_swap instead of ds_bpermute (no LDS round trips)
# baseline (speedup 1.0000x reference)
; __device__ __forceinline__ unsigned cvt_pk_bf16(float lo, float hi) { f32x2 v = {lo, hi}; bf16x2_t b = __builtin_convertvector(v, bf16x2_t); return __builtin_bit_cast(unsigned, b); }
;     __device__ __forceinline__ void operator()(ACC_T, const Unit& u, int wr, int wc, int fr, int fq) const {
;     ...
;             float sc = 1.f; if (u.pn < 2 || u.pn == 6 || u.pn == 7) sc = 0.125f * LOG2E; else if (u.pn >= 12) sc = 0.08838834764831845f * LOG2E;
;             const int col0 = u.pn * BM + cw;
; #pragma unroll
;             for (int ai = 0; ai < 2; ++ai)
; #pragma unroll
;                 for (int m = 0; m < 4; ++m) { bf16_t* rowp = P + (size_t)(row0 + ai * HALF + m * 16) * PW + col0;
; #pragma unroll
;                     for (int bj = 0; bj < 2; ++bj) { const f32x4 v0 = acc[ai][bj][m][0] * sc, v1 = acc[ai][bj][m][1] * sc;
;                         u32x4 w; w.x = cvt_pk_bf16(v0[0], v0[1]); w.y = cvt_pk_bf16(v0[2], v0[3]); w.z = cvt_pk_bf16(v1[0], v1[1]); w.w = cvt_pk_bf16(v1[2], v1[3]);
;                         *(u32x4*)(rowp + bj * HALF) = w;
;                         if (u.pn == 8 || u.pn == 9) {
;                             float q = (v0[0] * v0[0] + v0[1] * v0[1]) + (v0[2] * v0[2] + v0[3] * v0[3]) + (v1[0] * v1[0] + v1[1] * v1[1]) + (v1[2] * v1[2] + v1[3] * v1[3]);
;                             q += __shfl_xor(q, 16); q += __shfl_xor(q, 32);
;                             if (fq == 0) __hip_atomic_fetch_add(kn2 + (size_t)((u.pn - 8) * 4 + bj * 2 + (wc >> 1)) * T + (row0 + ai * HALF + m * 16), q, __ATOMIC_RELAXED, __HIP_MEMORY_SCOPE_AGENT); } } }
.LBB0_305:
	s_andn2_b64 vcc, exec, s[0:1]
	s_cbranch_vccnz .LBB0_370
	s_cmp_lt_i32 s40, 2
	s_cselect_b64 s[0:1], -1, 0
	s_and_b32 s14, s40, -2
	s_cmp_eq_u32 s14, 6
	s_cselect_b64 s[2:3], -1, 0
	s_or_b64 vcc, s[0:1], s[2:3]
	s_cmp_gt_u32 s40, 11
	s_cselect_b64 s[0:1], -1, 0
	s_cmp_eq_u32 s14, 8
	v_cndmask_b32_e64 v0, 1.0, v227, s[0:1]
	s_cselect_b64 s[0:1], -1, 0
	s_lshl_b32 s2, s40, 2
	s_add_i32 s2, s2, s56
	s_cmp_lg_u32 s14, 8
	v_readlane_b32 s14, v251, 56
	v_readlane_b32 s15, v251, 57
	v_cndmask_b32_e32 v130, v0, v231, vcc
	v_lshl_or_b32 v132, s40, 8, v178
	v_mov_b64_e32 v[134:135], s[14:15]
	s_movk_i32 s3, 0x1c00
	v_ashrrev_i32_e32 v133, 31, v132
	v_mad_i64_i32 v[134:135], s[14:15], v158, s3, v[134:135]
	v_pk_mul_f32 v[128:129], v[130:131], v[128:129] op_sel_hi:[0,1]
	v_pk_mul_f32 v[126:127], v[130:131], v[126:127] op_sel_hi:[0,1]
	v_pk_mul_f32 v[124:125], v[130:131], v[124:125] op_sel_hi:[0,1]
	v_pk_mul_f32 v[122:123], v[130:131], v[122:123] op_sel_hi:[0,1]
	v_ashrrev_i32_e32 v159, 31, v158
	v_lshl_add_u64 v[134:135], v[132:133], 1, v[134:135]
	v_cvt_pk_bf16_f32 v136, v126, v127
	v_cvt_pk_bf16_f32 v137, v128, v129
	v_cvt_pk_bf16_f32 v138, v122, v123
	v_cvt_pk_bf16_f32 v139, v124, v125
	global_store_dwordx4 v[134:135], v[136:139], off
	s_cbranch_scc1 .LBB0_310
	v_mul_f32_e32 v0, v127, v127
	v_fmac_f32_e32 v0, v126, v126
	v_mul_f32_e32 v126, v129, v129
	v_fmac_f32_e32 v126, v128, v128
	v_mul_f32_e32 v123, v123, v123
	v_add_f32_e32 v0, v0, v126
	v_fmac_f32_e32 v123, v122, v122
	v_mul_f32_e32 v122, v125, v125
	v_add_f32_e32 v0, v0, v123
	v_fmac_f32_e32 v122, v124, v124
	v_and_b32_e32 v123, 64, v230
	v_add_f32_e32 v0, v122, v0
	v_mov_b32_e32 v122, v0
	s_nop 1
	v_permlane16_swap_b32_e32 v122, v0
	s_nop 0
	v_add_f32_e32 v0, v0, v122
	v_mov_b32_e32 v122, v0
	s_nop 1
	v_permlane32_swap_b32_e32 v122, v0
	s_nop 0
	s_and_saveexec_b64 s[14:15], s[36:37]
	s_cbranch_execz .LBB0_309
	s_lshl_b32 s3, s2, 16
	v_readlane_b32 s18, v252, 17
	s_add_u32 s18, s18, s3
	v_readlane_b32 s3, v252, 18
	s_addc_u32 s19, s3, 0
	v_lshl_add_u64 v[124:125], v[158:159], 2, s[18:19]
	s_waitcnt lgkmcnt(0)
	v_add_f32_e32 v0, v0, v122
	global_atomic_add_f32 v[124:125], v0, off

; __device__ __forceinline__ unsigned cvt_pk_bf16(float lo, float hi) { f32x2 v = {lo, hi}; bf16x2_t b = __builtin_convertvector(v, bf16x2_t); return __builtin_bit_cast(unsigned, b); }
;     __device__ __forceinline__ void operator()(ACC_T, const Unit& u, int wr, int wc, int fr, int fq) const {
;     ...
;                 for (int m = 0; m < 4; ++m) { bf16_t* rowp = P + (size_t)(row0 + ai * HALF + m * 16) * PW + col0;
; #pragma unroll
;                     for (int bj = 0; bj < 2; ++bj) { const f32x4 v0 = acc[ai][bj][m][0] * sc, v1 = acc[ai][bj][m][1] * sc;
;                         u32x4 w; w.x = cvt_pk_bf16(v0[0], v0[1]); w.y = cvt_pk_bf16(v0[2], v0[3]); w.z = cvt_pk_bf16(v1[0], v1[1]); w.w = cvt_pk_bf16(v1[2], v1[3]);
;                         *(u32x4*)(rowp + bj * HALF) = w;
;                         if (u.pn == 8 || u.pn == 9) {
;                             float q = (v0[0] * v0[0] + v0[1] * v0[1]) + (v0[2] * v0[2] + v0[3] * v0[3]) + (v1[0] * v1[0] + v1[1] * v1[1]) + (v1[2] * v1[2] + v1[3] * v1[3]);
;                             q += __shfl_xor(q, 16); q += __shfl_xor(q, 32);
;                             if (fq == 0) __hip_atomic_fetch_add(kn2 + (size_t)((u.pn - 8) * 4 + bj * 2 + (wc >> 1)) * T + (row0 + ai * HALF + m * 16), q, __ATOMIC_RELAXED, __HIP_MEMORY_SCOPE_AGENT); } } }
.LBB0_310:
	v_mov_b32_e32 v131, v130
	s_waitcnt lgkmcnt(0)
	v_mov_b32_e32 v122, v130
	v_mov_b32_e32 v123, v130
	v_pk_mul_f32 v[120:121], v[122:123], v[120:121]
	v_pk_mul_f32 v[118:119], v[130:131], v[118:119]
	v_pk_mul_f32 v[116:117], v[122:123], v[116:117]
	v_pk_mul_f32 v[114:115], v[130:131], v[114:115]
	v_cndmask_b32_e64 v0, 0, 1, s[0:1]
	v_cvt_pk_bf16_f32 v124, v118, v119
	v_cvt_pk_bf16_f32 v125, v120, v121
	v_cvt_pk_bf16_f32 v126, v114, v115
	v_cvt_pk_bf16_f32 v127, v116, v117
	v_cmp_ne_u32_e64 s[40:41], 1, v0
	s_andn2_b64 vcc, exec, s[0:1]
	global_store_dwordx4 v[134:135], v[124:127], off offset:256
	s_cbranch_vccnz .LBB0_314
	v_mul_f32_e32 v0, v119, v119
	v_fmac_f32_e32 v0, v118, v118
	v_mul_f32_e32 v118, v121, v121
	v_fmac_f32_e32 v118, v120, v120
	v_mul_f32_e32 v115, v115, v115
	v_add_f32_e32 v0, v0, v118
	v_fmac_f32_e32 v115, v114, v114
	v_mul_f32_e32 v114, v117, v117
	v_add_f32_e32 v0, v0, v115
	v_fmac_f32_e32 v114, v116, v116
	v_and_b32_e32 v115, 64, v230
	v_add_f32_e32 v0, v114, v0
	v_mov_b32_e32 v114, v0
	s_nop 1
	v_permlane16_swap_b32_e32 v114, v0
	s_nop 0
	v_add_f32_e32 v0, v0, v114
	v_mov_b32_e32 v114, v0
	s_nop 1
	v_permlane32_swap_b32_e32 v114, v0
	s_nop 0
	s_and_saveexec_b64 s[0:1], s[36:37]
	s_cbranch_execz .LBB0_313
	s_lshl_b32 s3, s2, 16
	v_readlane_b32 s14, v252, 17
	s_add_u32 s14, s14, s3
	v_readlane_b32 s3, v252, 18
	s_addc_u32 s15, s3, 0
	v_lshl_add_u64 v[116:117], v[158:159], 2, s[14:15]
	s_waitcnt lgkmcnt(0)
	v_add_f32_e32 v0, v0, v114
	v_add_co_u32_e32 v114, vcc, 0x20000, v116
	s_nop 1
	v_addc_co_u32_e32 v115, vcc, 0, v117, vcc
	global_atomic_add_f32 v[114:115], v0, off

; __device__ __forceinline__ unsigned cvt_pk_bf16(float lo, float hi) { f32x2 v = {lo, hi}; bf16x2_t b = __builtin_convertvector(v, bf16x2_t); return __builtin_bit_cast(unsigned, b); }
;     __device__ __forceinline__ void operator()(ACC_T, const Unit& u, int wr, int wc, int fr, int fq) const {
;     ...
;                 for (int m = 0; m < 4; ++m) { bf16_t* rowp = P + (size_t)(row0 + ai * HALF + m * 16) * PW + col0;
; #pragma unroll
;                     for (int bj = 0; bj < 2; ++bj) { const f32x4 v0 = acc[ai][bj][m][0] * sc, v1 = acc[ai][bj][m][1] * sc;
;                         u32x4 w; w.x = cvt_pk_bf16(v0[0], v0[1]); w.y = cvt_pk_bf16(v0[2], v0[3]); w.z = cvt_pk_bf16(v1[0], v1[1]); w.w = cvt_pk_bf16(v1[2], v1[3]);
;                         *(u32x4*)(rowp + bj * HALF) = w;
;                         if (u.pn == 8 || u.pn == 9) {
;                             float q = (v0[0] * v0[0] + v0[1] * v0[1]) + (v0[2] * v0[2] + v0[3] * v0[3]) + (v1[0] * v1[0] + v1[1] * v1[1]) + (v1[2] * v1[2] + v1[3] * v1[3]);
;                             q += __shfl_xor(q, 16); q += __shfl_xor(q, 32);
;                             if (fq == 0) __hip_atomic_fetch_add(kn2 + (size_t)((u.pn - 8) * 4 + bj * 2 + (wc >> 1)) * T + (row0 + ai * HALF + m * 16), q, __ATOMIC_RELAXED, __HIP_MEMORY_SCOPE_AGENT); } } }
.LBB0_314:
	v_readlane_b32 s0, v251, 56
	v_readlane_b32 s1, v251, 57
	v_pk_mul_f32 v[112:113], v[122:123], v[112:113]
	v_pk_mul_f32 v[110:111], v[130:131], v[110:111]
	s_waitcnt lgkmcnt(0)
	v_mov_b64_e32 v[114:115], s[0:1]
	s_movk_i32 s0, 0x1c00
	v_mad_i64_i32 v[114:115], s[0:1], v168, s0, v[114:115]
	v_pk_mul_f32 v[108:109], v[122:123], v[108:109]
	v_pk_mul_f32 v[106:107], v[130:131], v[106:107]
	v_lshl_add_u64 v[114:115], v[132:133], 1, v[114:115]
	v_cvt_pk_bf16_f32 v116, v110, v111
	v_cvt_pk_bf16_f32 v117, v112, v113
	v_cvt_pk_bf16_f32 v118, v106, v107
	v_cvt_pk_bf16_f32 v119, v108, v109
	s_and_b64 vcc, exec, s[40:41]
	global_store_dwordx4 v[114:115], v[116:119], off
	s_cbranch_vccnz .LBB0_318
	v_mul_f32_e32 v0, v111, v111
	v_fmac_f32_e32 v0, v110, v110
	v_mul_f32_e32 v110, v113, v113
	v_fmac_f32_e32 v110, v112, v112
	v_mul_f32_e32 v107, v107, v107
	v_add_f32_e32 v0, v0, v110
	v_fmac_f32_e32 v107, v106, v106
	v_mul_f32_e32 v106, v109, v109
	v_add_f32_e32 v0, v0, v107
	v_fmac_f32_e32 v106, v108, v108
	v_and_b32_e32 v107, 64, v230
	v_add_f32_e32 v0, v106, v0
	v_mov_b32_e32 v106, v0
	s_nop 1
	v_permlane16_swap_b32_e32 v106, v0
	s_nop 0
	v_add_f32_e32 v0, v0, v106
	v_mov_b32_e32 v106, v0
	s_nop 1
	v_permlane32_swap_b32_e32 v106, v0
	s_nop 0
	s_and_saveexec_b64 s[0:1], s[36:37]
	s_cbranch_execz .LBB0_317
	s_lshl_b32 s3, s2, 16
	v_readlane_b32 s14, v252, 17
	s_add_u32 s14, s14, s3
	v_readlane_b32 s3, v252, 18
	s_addc_u32 s15, s3, 0
	v_lshl_add_u64 v[108:109], v[158:159], 2, s[14:15]
	s_waitcnt lgkmcnt(0)
	v_add_f32_e32 v0, v0, v106
	global_atomic_add_f32 v[108:109], v0, off offset:64

; __device__ __forceinline__ unsigned cvt_pk_bf16(float lo, float hi) { f32x2 v = {lo, hi}; bf16x2_t b = __builtin_convertvector(v, bf16x2_t); return __builtin_bit_cast(unsigned, b); }
;     __device__ __forceinline__ void operator()(ACC_T, const Unit& u, int wr, int wc, int fr, int fq) const {
;     ...
;                 for (int m = 0; m < 4; ++m) { bf16_t* rowp = P + (size_t)(row0 + ai * HALF + m * 16) * PW + col0;
; #pragma unroll
;                     for (int bj = 0; bj < 2; ++bj) { const f32x4 v0 = acc[ai][bj][m][0] * sc, v1 = acc[ai][bj][m][1] * sc;
;                         u32x4 w; w.x = cvt_pk_bf16(v0[0], v0[1]); w.y = cvt_pk_bf16(v0[2], v0[3]); w.z = cvt_pk_bf16(v1[0], v1[1]); w.w = cvt_pk_bf16(v1[2], v1[3]);
;                         *(u32x4*)(rowp + bj * HALF) = w;
;                         if (u.pn == 8 || u.pn == 9) {
;                             float q = (v0[0] * v0[0] + v0[1] * v0[1]) + (v0[2] * v0[2] + v0[3] * v0[3]) + (v1[0] * v1[0] + v1[1] * v1[1]) + (v1[2] * v1[2] + v1[3] * v1[3]);
;                             q += __shfl_xor(q, 16); q += __shfl_xor(q, 32);
;                             if (fq == 0) __hip_atomic_fetch_add(kn2 + (size_t)((u.pn - 8) * 4 + bj * 2 + (wc >> 1)) * T + (row0 + ai * HALF + m * 16), q, __ATOMIC_RELAXED, __HIP_MEMORY_SCOPE_AGENT); } } }
.LBB0_318:
	s_waitcnt lgkmcnt(0)
	v_mov_b32_e32 v106, v130
	v_mov_b32_e32 v107, v130
	v_pk_mul_f32 v[104:105], v[106:107], v[104:105]
	v_pk_mul_f32 v[102:103], v[130:131], v[102:103]
	v_pk_mul_f32 v[100:101], v[106:107], v[100:101]
	v_pk_mul_f32 v[98:99], v[130:131], v[98:99]
	v_cvt_pk_bf16_f32 v108, v102, v103
	v_cvt_pk_bf16_f32 v109, v104, v105
	v_cvt_pk_bf16_f32 v110, v98, v99
	v_cvt_pk_bf16_f32 v111, v100, v101
	s_and_b64 vcc, exec, s[40:41]
	global_store_dwordx4 v[114:115], v[108:111], off offset:256
	s_cbranch_vccnz .LBB0_322
	v_mul_f32_e32 v0, v103, v103
	v_fmac_f32_e32 v0, v102, v102
	v_mul_f32_e32 v102, v105, v105
	v_fmac_f32_e32 v102, v104, v104
	v_mul_f32_e32 v99, v99, v99
	v_add_f32_e32 v0, v0, v102
	v_fmac_f32_e32 v99, v98, v98
	v_mul_f32_e32 v98, v101, v101
	v_add_f32_e32 v0, v0, v99
	v_fmac_f32_e32 v98, v100, v100
	v_and_b32_e32 v99, 64, v230
	v_add_f32_e32 v0, v98, v0
	v_mov_b32_e32 v98, v0
	s_nop 1
	v_permlane16_swap_b32_e32 v98, v0
	s_nop 0
	v_add_f32_e32 v0, v0, v98
	v_mov_b32_e32 v98, v0
	s_nop 1
	v_permlane32_swap_b32_e32 v98, v0
	s_nop 0
	s_and_saveexec_b64 s[0:1], s[36:37]
	s_cbranch_execz .LBB0_321
	s_lshl_b32 s3, s2, 16
	v_readlane_b32 s14, v252, 17
	s_add_u32 s14, s14, s3
	v_readlane_b32 s3, v252, 18
	v_ashrrev_i32_e32 v169, 31, v168
	s_addc_u32 s15, s3, 0
	v_lshl_add_u64 v[100:101], v[168:169], 2, s[14:15]
	s_waitcnt lgkmcnt(0)
	v_add_f32_e32 v0, v0, v98
	v_add_co_u32_e32 v98, vcc, 0x20000, v100
	s_nop 1
	v_addc_co_u32_e32 v99, vcc, 0, v101, vcc
	global_atomic_add_f32 v[98:99], v0, off

; __device__ __forceinline__ unsigned cvt_pk_bf16(float lo, float hi) { f32x2 v = {lo, hi}; bf16x2_t b = __builtin_convertvector(v, bf16x2_t); return __builtin_bit_cast(unsigned, b); }
;     __device__ __forceinline__ void operator()(ACC_T, const Unit& u, int wr, int wc, int fr, int fq) const {
;     ...
;                 for (int m = 0; m < 4; ++m) { bf16_t* rowp = P + (size_t)(row0 + ai * HALF + m * 16) * PW + col0;
; #pragma unroll
;                     for (int bj = 0; bj < 2; ++bj) { const f32x4 v0 = acc[ai][bj][m][0] * sc, v1 = acc[ai][bj][m][1] * sc;
;                         u32x4 w; w.x = cvt_pk_bf16(v0[0], v0[1]); w.y = cvt_pk_bf16(v0[2], v0[3]); w.z = cvt_pk_bf16(v1[0], v1[1]); w.w = cvt_pk_bf16(v1[2], v1[3]);
;                         *(u32x4*)(rowp + bj * HALF) = w;
;                         if (u.pn == 8 || u.pn == 9) {
;                             float q = (v0[0] * v0[0] + v0[1] * v0[1]) + (v0[2] * v0[2] + v0[3] * v0[3]) + (v1[0] * v1[0] + v1[1] * v1[1]) + (v1[2] * v1[2] + v1[3] * v1[3]);
;                             q += __shfl_xor(q, 16); q += __shfl_xor(q, 32);
;                             if (fq == 0) __hip_atomic_fetch_add(kn2 + (size_t)((u.pn - 8) * 4 + bj * 2 + (wc >> 1)) * T + (row0 + ai * HALF + m * 16), q, __ATOMIC_RELAXED, __HIP_MEMORY_SCOPE_AGENT); } } }
.LBB0_322:
	v_readlane_b32 s0, v251, 56
	v_readlane_b32 s1, v251, 57
	v_pk_mul_f32 v[96:97], v[106:107], v[96:97]
	v_pk_mul_f32 v[94:95], v[130:131], v[94:95]
	s_waitcnt lgkmcnt(0)
	v_mov_b64_e32 v[98:99], s[0:1]
	s_movk_i32 s0, 0x1c00
	v_mad_i64_i32 v[98:99], s[0:1], v166, s0, v[98:99]
	v_pk_mul_f32 v[92:93], v[106:107], v[92:93]
	v_pk_mul_f32 v[90:91], v[130:131], v[90:91]
	v_lshl_add_u64 v[98:99], v[132:133], 1, v[98:99]
	v_cvt_pk_bf16_f32 v100, v94, v95
	v_cvt_pk_bf16_f32 v101, v96, v97
	v_cvt_pk_bf16_f32 v102, v90, v91
	v_cvt_pk_bf16_f32 v103, v92, v93
	s_and_b64 vcc, exec, s[40:41]
	global_store_dwordx4 v[98:99], v[100:103], off
	s_cbranch_vccnz .LBB0_326
	v_mul_f32_e32 v0, v95, v95
	v_fmac_f32_e32 v0, v94, v94
	v_mul_f32_e32 v94, v97, v97
	v_fmac_f32_e32 v94, v96, v96
	v_mul_f32_e32 v91, v91, v91
	v_add_f32_e32 v0, v0, v94
	v_fmac_f32_e32 v91, v90, v90
	v_mul_f32_e32 v90, v93, v93
	v_add_f32_e32 v0, v0, v91
	v_fmac_f32_e32 v90, v92, v92
	v_and_b32_e32 v91, 64, v230
	v_add_f32_e32 v0, v90, v0
	v_mov_b32_e32 v90, v0
	s_nop 1
	v_permlane16_swap_b32_e32 v90, v0
	s_nop 0
	v_add_f32_e32 v0, v0, v90
	v_mov_b32_e32 v90, v0
	s_nop 1
	v_permlane32_swap_b32_e32 v90, v0
	s_nop 0
	s_and_saveexec_b64 s[0:1], s[36:37]
	s_cbranch_execz .LBB0_325
	s_lshl_b32 s3, s2, 16
	v_readlane_b32 s14, v252, 17
	s_add_u32 s14, s14, s3
	v_readlane_b32 s3, v252, 18
	s_addc_u32 s15, s3, 0
	v_lshl_add_u64 v[92:93], v[158:159], 2, s[14:15]
	s_waitcnt lgkmcnt(0)
	v_add_f32_e32 v0, v0, v90
	global_atomic_add_f32 v[92:93], v0, off offset:128

; __device__ __forceinline__ unsigned cvt_pk_bf16(float lo, float hi) { f32x2 v = {lo, hi}; bf16x2_t b = __builtin_convertvector(v, bf16x2_t); return __builtin_bit_cast(unsigned, b); }
;     __device__ __forceinline__ void operator()(ACC_T, const Unit& u, int wr, int wc, int fr, int fq) const {
;     ...
;                 for (int m = 0; m < 4; ++m) { bf16_t* rowp = P + (size_t)(row0 + ai * HALF + m * 16) * PW + col0;
; #pragma unroll
;                     for (int bj = 0; bj < 2; ++bj) { const f32x4 v0 = acc[ai][bj][m][0] * sc, v1 = acc[ai][bj][m][1] * sc;
;                         u32x4 w; w.x = cvt_pk_bf16(v0[0], v0[1]); w.y = cvt_pk_bf16(v0[2], v0[3]); w.z = cvt_pk_bf16(v1[0], v1[1]); w.w = cvt_pk_bf16(v1[2], v1[3]);
;                         *(u32x4*)(rowp + bj * HALF) = w;
;                         if (u.pn == 8 || u.pn == 9) {
;                             float q = (v0[0] * v0[0] + v0[1] * v0[1]) + (v0[2] * v0[2] + v0[3] * v0[3]) + (v1[0] * v1[0] + v1[1] * v1[1]) + (v1[2] * v1[2] + v1[3] * v1[3]);
;                             q += __shfl_xor(q, 16); q += __shfl_xor(q, 32);
;                             if (fq == 0) __hip_atomic_fetch_add(kn2 + (size_t)((u.pn - 8) * 4 + bj * 2 + (wc >> 1)) * T + (row0 + ai * HALF + m * 16), q, __ATOMIC_RELAXED, __HIP_MEMORY_SCOPE_AGENT); } } }
.LBB0_326:
	s_waitcnt lgkmcnt(0)
	v_mov_b32_e32 v90, v130
	v_mov_b32_e32 v91, v130
	v_pk_mul_f32 v[88:89], v[90:91], v[88:89]
	v_pk_mul_f32 v[86:87], v[130:131], v[86:87]
	v_pk_mul_f32 v[84:85], v[90:91], v[84:85]
	v_pk_mul_f32 v[82:83], v[130:131], v[82:83]
	v_cvt_pk_bf16_f32 v92, v86, v87
	v_cvt_pk_bf16_f32 v93, v88, v89
	v_cvt_pk_bf16_f32 v94, v82, v83
	v_cvt_pk_bf16_f32 v95, v84, v85
	s_and_b64 vcc, exec, s[40:41]
	global_store_dwordx4 v[98:99], v[92:95], off offset:256
	s_cbranch_vccnz .LBB0_330
	v_mul_f32_e32 v0, v87, v87
	v_fmac_f32_e32 v0, v86, v86
	v_mul_f32_e32 v86, v89, v89
	v_fmac_f32_e32 v86, v88, v88
	v_mul_f32_e32 v83, v83, v83
	v_add_f32_e32 v0, v0, v86
	v_fmac_f32_e32 v83, v82, v82
	v_mul_f32_e32 v82, v85, v85
	v_add_f32_e32 v0, v0, v83
	v_fmac_f32_e32 v82, v84, v84
	v_and_b32_e32 v83, 64, v230
	v_add_f32_e32 v0, v82, v0
	v_mov_b32_e32 v82, v0
	s_nop 1
	v_permlane16_swap_b32_e32 v82, v0
	s_nop 0
	v_add_f32_e32 v0, v0, v82
	v_mov_b32_e32 v82, v0
	s_nop 1
	v_permlane32_swap_b32_e32 v82, v0
	s_nop 0
	s_and_saveexec_b64 s[0:1], s[36:37]
	s_cbranch_execz .LBB0_329
	s_lshl_b32 s3, s2, 16
	v_readlane_b32 s14, v252, 17
	s_add_u32 s14, s14, s3
	v_readlane_b32 s3, v252, 18
	v_ashrrev_i32_e32 v167, 31, v166
	s_addc_u32 s15, s3, 0
	v_lshl_add_u64 v[84:85], v[166:167], 2, s[14:15]
	s_waitcnt lgkmcnt(0)
	v_add_f32_e32 v0, v0, v82
	v_add_co_u32_e32 v82, vcc, 0x20000, v84
	s_nop 1
	v_addc_co_u32_e32 v83, vcc, 0, v85, vcc
	global_atomic_add_f32 v[82:83], v0, off

; __device__ __forceinline__ unsigned cvt_pk_bf16(float lo, float hi) { f32x2 v = {lo, hi}; bf16x2_t b = __builtin_convertvector(v, bf16x2_t); return __builtin_bit_cast(unsigned, b); }
;     __device__ __forceinline__ void operator()(ACC_T, const Unit& u, int wr, int wc, int fr, int fq) const {
;     ...
;                 for (int m = 0; m < 4; ++m) { bf16_t* rowp = P + (size_t)(row0 + ai * HALF + m * 16) * PW + col0;
; #pragma unroll
;                     for (int bj = 0; bj < 2; ++bj) { const f32x4 v0 = acc[ai][bj][m][0] * sc, v1 = acc[ai][bj][m][1] * sc;
;                         u32x4 w; w.x = cvt_pk_bf16(v0[0], v0[1]); w.y = cvt_pk_bf16(v0[2], v0[3]); w.z = cvt_pk_bf16(v1[0], v1[1]); w.w = cvt_pk_bf16(v1[2], v1[3]);
;                         *(u32x4*)(rowp + bj * HALF) = w;
;                         if (u.pn == 8 || u.pn == 9) {
;                             float q = (v0[0] * v0[0] + v0[1] * v0[1]) + (v0[2] * v0[2] + v0[3] * v0[3]) + (v1[0] * v1[0] + v1[1] * v1[1]) + (v1[2] * v1[2] + v1[3] * v1[3]);
;                             q += __shfl_xor(q, 16); q += __shfl_xor(q, 32);
;                             if (fq == 0) __hip_atomic_fetch_add(kn2 + (size_t)((u.pn - 8) * 4 + bj * 2 + (wc >> 1)) * T + (row0 + ai * HALF + m * 16), q, __ATOMIC_RELAXED, __HIP_MEMORY_SCOPE_AGENT); } } }
.LBB0_330:
	v_readlane_b32 s0, v251, 56
	v_readlane_b32 s1, v251, 57
	v_pk_mul_f32 v[80:81], v[90:91], v[80:81]
	v_pk_mul_f32 v[78:79], v[130:131], v[78:79]
	s_waitcnt lgkmcnt(0)
	v_mov_b64_e32 v[82:83], s[0:1]
	s_movk_i32 s0, 0x1c00
	v_mad_i64_i32 v[82:83], s[0:1], v164, s0, v[82:83]
	v_pk_mul_f32 v[76:77], v[90:91], v[76:77]
	v_pk_mul_f32 v[74:75], v[130:131], v[74:75]
	v_lshl_add_u64 v[82:83], v[132:133], 1, v[82:83]
	v_cvt_pk_bf16_f32 v84, v78, v79
	v_cvt_pk_bf16_f32 v85, v80, v81
	v_cvt_pk_bf16_f32 v86, v74, v75
	v_cvt_pk_bf16_f32 v87, v76, v77
	s_and_b64 vcc, exec, s[40:41]
	global_store_dwordx4 v[82:83], v[84:87], off
	s_cbranch_vccnz .LBB0_334
	v_mul_f32_e32 v0, v79, v79
	v_fmac_f32_e32 v0, v78, v78
	v_mul_f32_e32 v78, v81, v81
	v_fmac_f32_e32 v78, v80, v80
	v_mul_f32_e32 v75, v75, v75
	v_add_f32_e32 v0, v0, v78
	v_fmac_f32_e32 v75, v74, v74
	v_mul_f32_e32 v74, v77, v77
	v_add_f32_e32 v0, v0, v75
	v_fmac_f32_e32 v74, v76, v76
	v_and_b32_e32 v75, 64, v230
	v_add_f32_e32 v0, v74, v0
	v_mov_b32_e32 v74, v0
	s_nop 1
	v_permlane16_swap_b32_e32 v74, v0
	s_nop 0
	v_add_f32_e32 v0, v0, v74
	v_mov_b32_e32 v74, v0
	s_nop 1
	v_permlane32_swap_b32_e32 v74, v0
	s_nop 0
	s_and_saveexec_b64 s[0:1], s[36:37]
	s_cbranch_execz .LBB0_333
	s_lshl_b32 s3, s2, 16
	v_readlane_b32 s14, v252, 17
	s_add_u32 s14, s14, s3
	v_readlane_b32 s3, v252, 18
	s_addc_u32 s15, s3, 0
	v_lshl_add_u64 v[76:77], v[158:159], 2, s[14:15]
	s_waitcnt lgkmcnt(0)
	v_add_f32_e32 v0, v0, v74
	global_atomic_add_f32 v[76:77], v0, off offset:192

; __device__ __forceinline__ unsigned cvt_pk_bf16(float lo, float hi) { f32x2 v = {lo, hi}; bf16x2_t b = __builtin_convertvector(v, bf16x2_t); return __builtin_bit_cast(unsigned, b); }
;     __device__ __forceinline__ void operator()(ACC_T, const Unit& u, int wr, int wc, int fr, int fq) const {
;     ...
;                 for (int m = 0; m < 4; ++m) { bf16_t* rowp = P + (size_t)(row0 + ai * HALF + m * 16) * PW + col0;
; #pragma unroll
;                     for (int bj = 0; bj < 2; ++bj) { const f32x4 v0 = acc[ai][bj][m][0] * sc, v1 = acc[ai][bj][m][1] * sc;
;                         u32x4 w; w.x = cvt_pk_bf16(v0[0], v0[1]); w.y = cvt_pk_bf16(v0[2], v0[3]); w.z = cvt_pk_bf16(v1[0], v1[1]); w.w = cvt_pk_bf16(v1[2], v1[3]);
;                         *(u32x4*)(rowp + bj * HALF) = w;
;                         if (u.pn == 8 || u.pn == 9) {
;                             float q = (v0[0] * v0[0] + v0[1] * v0[1]) + (v0[2] * v0[2] + v0[3] * v0[3]) + (v1[0] * v1[0] + v1[1] * v1[1]) + (v1[2] * v1[2] + v1[3] * v1[3]);
;                             q += __shfl_xor(q, 16); q += __shfl_xor(q, 32);
;                             if (fq == 0) __hip_atomic_fetch_add(kn2 + (size_t)((u.pn - 8) * 4 + bj * 2 + (wc >> 1)) * T + (row0 + ai * HALF + m * 16), q, __ATOMIC_RELAXED, __HIP_MEMORY_SCOPE_AGENT); } } }
.LBB0_334:
	s_waitcnt lgkmcnt(0)
	v_mov_b32_e32 v74, v130
	v_mov_b32_e32 v75, v130
	v_pk_mul_f32 v[72:73], v[74:75], v[72:73]
	v_pk_mul_f32 v[70:71], v[130:131], v[70:71]
	v_pk_mul_f32 v[68:69], v[74:75], v[68:69]
	v_pk_mul_f32 v[66:67], v[130:131], v[66:67]
	v_cvt_pk_bf16_f32 v76, v70, v71
	v_cvt_pk_bf16_f32 v77, v72, v73
	v_cvt_pk_bf16_f32 v78, v66, v67
	v_cvt_pk_bf16_f32 v79, v68, v69
	s_and_b64 vcc, exec, s[40:41]
	global_store_dwordx4 v[82:83], v[76:79], off offset:256
	s_cbranch_vccnz .LBB0_338
	v_mul_f32_e32 v0, v71, v71
	v_fmac_f32_e32 v0, v70, v70
	v_mul_f32_e32 v70, v73, v73
	v_fmac_f32_e32 v70, v72, v72
	v_mul_f32_e32 v67, v67, v67
	v_add_f32_e32 v0, v0, v70
	v_fmac_f32_e32 v67, v66, v66
	v_mul_f32_e32 v66, v69, v69
	v_add_f32_e32 v0, v0, v67
	v_fmac_f32_e32 v66, v68, v68
	v_and_b32_e32 v67, 64, v230
	v_add_f32_e32 v0, v66, v0
	v_mov_b32_e32 v66, v0
	s_nop 1
	v_permlane16_swap_b32_e32 v66, v0
	s_nop 0
	v_add_f32_e32 v0, v0, v66
	v_mov_b32_e32 v66, v0
	s_nop 1
	v_permlane32_swap_b32_e32 v66, v0
	s_nop 0
	s_and_saveexec_b64 s[0:1], s[36:37]
	s_cbranch_execz .LBB0_337
	s_lshl_b32 s3, s2, 16
	v_readlane_b32 s14, v252, 17
	s_add_u32 s14, s14, s3
	v_readlane_b32 s3, v252, 18
	v_ashrrev_i32_e32 v165, 31, v164
	s_addc_u32 s15, s3, 0
	v_lshl_add_u64 v[68:69], v[164:165], 2, s[14:15]
	s_waitcnt lgkmcnt(0)
	v_add_f32_e32 v0, v0, v66
	v_add_co_u32_e32 v66, vcc, 0x20000, v68
	s_nop 1
	v_addc_co_u32_e32 v67, vcc, 0, v69, vcc
	global_atomic_add_f32 v[66:67], v0, off

; __device__ __forceinline__ unsigned cvt_pk_bf16(float lo, float hi) { f32x2 v = {lo, hi}; bf16x2_t b = __builtin_convertvector(v, bf16x2_t); return __builtin_bit_cast(unsigned, b); }
;     __device__ __forceinline__ void operator()(ACC_T, const Unit& u, int wr, int wc, int fr, int fq) const {
;     ...
;                 for (int m = 0; m < 4; ++m) { bf16_t* rowp = P + (size_t)(row0 + ai * HALF + m * 16) * PW + col0;
; #pragma unroll
;                     for (int bj = 0; bj < 2; ++bj) { const f32x4 v0 = acc[ai][bj][m][0] * sc, v1 = acc[ai][bj][m][1] * sc;
;                         u32x4 w; w.x = cvt_pk_bf16(v0[0], v0[1]); w.y = cvt_pk_bf16(v0[2], v0[3]); w.z = cvt_pk_bf16(v1[0], v1[1]); w.w = cvt_pk_bf16(v1[2], v1[3]);
;                         *(u32x4*)(rowp + bj * HALF) = w;
;                         if (u.pn == 8 || u.pn == 9) {
;                             float q = (v0[0] * v0[0] + v0[1] * v0[1]) + (v0[2] * v0[2] + v0[3] * v0[3]) + (v1[0] * v1[0] + v1[1] * v1[1]) + (v1[2] * v1[2] + v1[3] * v1[3]);
;                             q += __shfl_xor(q, 16); q += __shfl_xor(q, 32);
;                             if (fq == 0) __hip_atomic_fetch_add(kn2 + (size_t)((u.pn - 8) * 4 + bj * 2 + (wc >> 1)) * T + (row0 + ai * HALF + m * 16), q, __ATOMIC_RELAXED, __HIP_MEMORY_SCOPE_AGENT); } } }
.LBB0_338:
	v_readlane_b32 s0, v251, 56
	v_readlane_b32 s1, v251, 57
	v_pk_mul_f32 v[64:65], v[74:75], v[64:65]
	v_pk_mul_f32 v[62:63], v[130:131], v[62:63]
	s_waitcnt lgkmcnt(0)
	v_mov_b64_e32 v[66:67], s[0:1]
	s_movk_i32 s0, 0x1c00
	v_mad_i64_i32 v[66:67], s[0:1], v162, s0, v[66:67]
	v_pk_mul_f32 v[60:61], v[74:75], v[60:61]
	v_pk_mul_f32 v[58:59], v[130:131], v[58:59]
	v_lshl_add_u64 v[66:67], v[132:133], 1, v[66:67]
	v_cvt_pk_bf16_f32 v68, v62, v63
	v_cvt_pk_bf16_f32 v69, v64, v65
	v_cvt_pk_bf16_f32 v70, v58, v59
	v_cvt_pk_bf16_f32 v71, v60, v61
	s_and_b64 vcc, exec, s[40:41]
	global_store_dwordx4 v[66:67], v[68:71], off
	s_cbranch_vccnz .LBB0_342
	v_mul_f32_e32 v0, v63, v63
	v_fmac_f32_e32 v0, v62, v62
	v_mul_f32_e32 v62, v65, v65
	v_fmac_f32_e32 v62, v64, v64
	v_mul_f32_e32 v59, v59, v59
	v_add_f32_e32 v0, v0, v62
	v_fmac_f32_e32 v59, v58, v58
	v_mul_f32_e32 v58, v61, v61
	v_add_f32_e32 v0, v0, v59
	v_fmac_f32_e32 v58, v60, v60
	v_and_b32_e32 v59, 64, v230
	v_add_f32_e32 v0, v58, v0
	v_mov_b32_e32 v58, v0
	s_nop 1
	v_permlane16_swap_b32_e32 v58, v0
	s_nop 0
	v_add_f32_e32 v0, v0, v58
	v_mov_b32_e32 v58, v0
	s_nop 1
	v_permlane32_swap_b32_e32 v58, v0
	s_nop 0
	s_and_saveexec_b64 s[0:1], s[36:37]
	s_cbranch_execz .LBB0_341
	s_lshl_b32 s3, s2, 16
	v_readlane_b32 s14, v252, 17
	s_add_u32 s14, s14, s3
	v_readlane_b32 s3, v252, 18
	s_addc_u32 s15, s3, 0
	v_lshl_add_u64 v[60:61], v[158:159], 2, s[14:15]
	s_waitcnt lgkmcnt(0)
	v_add_f32_e32 v0, v0, v58
	global_atomic_add_f32 v[60:61], v0, off offset:512

; __device__ __forceinline__ unsigned cvt_pk_bf16(float lo, float hi) { f32x2 v = {lo, hi}; bf16x2_t b = __builtin_convertvector(v, bf16x2_t); return __builtin_bit_cast(unsigned, b); }
;     __device__ __forceinline__ void operator()(ACC_T, const Unit& u, int wr, int wc, int fr, int fq) const {
;     ...
;                 for (int m = 0; m < 4; ++m) { bf16_t* rowp = P + (size_t)(row0 + ai * HALF + m * 16) * PW + col0;
; #pragma unroll
;                     for (int bj = 0; bj < 2; ++bj) { const f32x4 v0 = acc[ai][bj][m][0] * sc, v1 = acc[ai][bj][m][1] * sc;
;                         u32x4 w; w.x = cvt_pk_bf16(v0[0], v0[1]); w.y = cvt_pk_bf16(v0[2], v0[3]); w.z = cvt_pk_bf16(v1[0], v1[1]); w.w = cvt_pk_bf16(v1[2], v1[3]);
;                         *(u32x4*)(rowp + bj * HALF) = w;
;                         if (u.pn == 8 || u.pn == 9) {
;                             float q = (v0[0] * v0[0] + v0[1] * v0[1]) + (v0[2] * v0[2] + v0[3] * v0[3]) + (v1[0] * v1[0] + v1[1] * v1[1]) + (v1[2] * v1[2] + v1[3] * v1[3]);
;                             q += __shfl_xor(q, 16); q += __shfl_xor(q, 32);
;                             if (fq == 0) __hip_atomic_fetch_add(kn2 + (size_t)((u.pn - 8) * 4 + bj * 2 + (wc >> 1)) * T + (row0 + ai * HALF + m * 16), q, __ATOMIC_RELAXED, __HIP_MEMORY_SCOPE_AGENT); } } }
.LBB0_342:
	s_waitcnt lgkmcnt(0)
	v_mov_b32_e32 v58, v130
	v_mov_b32_e32 v59, v130
	v_pk_mul_f32 v[56:57], v[58:59], v[56:57]
	v_pk_mul_f32 v[54:55], v[130:131], v[54:55]
	v_pk_mul_f32 v[52:53], v[58:59], v[52:53]
	v_pk_mul_f32 v[50:51], v[130:131], v[50:51]
	v_cvt_pk_bf16_f32 v60, v54, v55
	v_cvt_pk_bf16_f32 v61, v56, v57
	v_cvt_pk_bf16_f32 v62, v50, v51
	v_cvt_pk_bf16_f32 v63, v52, v53
	s_and_b64 vcc, exec, s[40:41]
	global_store_dwordx4 v[66:67], v[60:63], off offset:256
	s_cbranch_vccnz .LBB0_346
	v_mul_f32_e32 v0, v55, v55
	v_fmac_f32_e32 v0, v54, v54
	v_mul_f32_e32 v54, v57, v57
	v_fmac_f32_e32 v54, v56, v56
	v_mul_f32_e32 v51, v51, v51
	v_add_f32_e32 v0, v0, v54
	v_fmac_f32_e32 v51, v50, v50
	v_mul_f32_e32 v50, v53, v53
	v_add_f32_e32 v0, v0, v51
	v_fmac_f32_e32 v50, v52, v52
	v_and_b32_e32 v51, 64, v230
	v_add_f32_e32 v0, v50, v0
	v_mov_b32_e32 v50, v0
	s_nop 1
	v_permlane16_swap_b32_e32 v50, v0
	s_nop 0
	v_add_f32_e32 v0, v0, v50
	v_mov_b32_e32 v50, v0
	s_nop 1
	v_permlane32_swap_b32_e32 v50, v0
	s_nop 0
	s_and_saveexec_b64 s[0:1], s[36:37]
	s_cbranch_execz .LBB0_345
	s_lshl_b32 s3, s2, 16
	v_readlane_b32 s14, v252, 17
	s_add_u32 s14, s14, s3
	v_readlane_b32 s3, v252, 18
	v_ashrrev_i32_e32 v163, 31, v162
	s_addc_u32 s15, s3, 0
	v_lshl_add_u64 v[52:53], v[162:163], 2, s[14:15]
	s_waitcnt lgkmcnt(0)
	v_add_f32_e32 v0, v0, v50
	v_add_co_u32_e32 v50, vcc, 0x20000, v52
	s_nop 1
	v_addc_co_u32_e32 v51, vcc, 0, v53, vcc
	global_atomic_add_f32 v[50:51], v0, off

; __device__ __forceinline__ unsigned cvt_pk_bf16(float lo, float hi) { f32x2 v = {lo, hi}; bf16x2_t b = __builtin_convertvector(v, bf16x2_t); return __builtin_bit_cast(unsigned, b); }
;     __device__ __forceinline__ void operator()(ACC_T, const Unit& u, int wr, int wc, int fr, int fq) const {
;     ...
;                 for (int m = 0; m < 4; ++m) { bf16_t* rowp = P + (size_t)(row0 + ai * HALF + m * 16) * PW + col0;
; #pragma unroll
;                     for (int bj = 0; bj < 2; ++bj) { const f32x4 v0 = acc[ai][bj][m][0] * sc, v1 = acc[ai][bj][m][1] * sc;
;                         u32x4 w; w.x = cvt_pk_bf16(v0[0], v0[1]); w.y = cvt_pk_bf16(v0[2], v0[3]); w.z = cvt_pk_bf16(v1[0], v1[1]); w.w = cvt_pk_bf16(v1[2], v1[3]);
;                         *(u32x4*)(rowp + bj * HALF) = w;
;                         if (u.pn == 8 || u.pn == 9) {
;                             float q = (v0[0] * v0[0] + v0[1] * v0[1]) + (v0[2] * v0[2] + v0[3] * v0[3]) + (v1[0] * v1[0] + v1[1] * v1[1]) + (v1[2] * v1[2] + v1[3] * v1[3]);
;                             q += __shfl_xor(q, 16); q += __shfl_xor(q, 32);
;                             if (fq == 0) __hip_atomic_fetch_add(kn2 + (size_t)((u.pn - 8) * 4 + bj * 2 + (wc >> 1)) * T + (row0 + ai * HALF + m * 16), q, __ATOMIC_RELAXED, __HIP_MEMORY_SCOPE_AGENT); } } }
.LBB0_346:
	v_readlane_b32 s0, v251, 56
	v_readlane_b32 s1, v251, 57
	v_pk_mul_f32 v[48:49], v[58:59], v[48:49]
	v_pk_mul_f32 v[46:47], v[130:131], v[46:47]
	s_waitcnt lgkmcnt(0)
	v_mov_b64_e32 v[50:51], s[0:1]
	s_movk_i32 s0, 0x1c00
	v_mad_i64_i32 v[50:51], s[0:1], v160, s0, v[50:51]
	v_pk_mul_f32 v[44:45], v[58:59], v[44:45]
	v_pk_mul_f32 v[42:43], v[130:131], v[42:43]
	v_lshl_add_u64 v[50:51], v[132:133], 1, v[50:51]
	v_cvt_pk_bf16_f32 v52, v46, v47
	v_cvt_pk_bf16_f32 v53, v48, v49
	v_cvt_pk_bf16_f32 v54, v42, v43
	v_cvt_pk_bf16_f32 v55, v44, v45
	s_and_b64 vcc, exec, s[40:41]
	global_store_dwordx4 v[50:51], v[52:55], off
	s_cbranch_vccnz .LBB0_350
	v_mul_f32_e32 v0, v47, v47
	v_fmac_f32_e32 v0, v46, v46
	v_mul_f32_e32 v46, v49, v49
	v_fmac_f32_e32 v46, v48, v48
	v_mul_f32_e32 v43, v43, v43
	v_add_f32_e32 v0, v0, v46
	v_fmac_f32_e32 v43, v42, v42
	v_mul_f32_e32 v42, v45, v45
	v_add_f32_e32 v0, v0, v43
	v_fmac_f32_e32 v42, v44, v44
	v_and_b32_e32 v43, 64, v230
	v_add_f32_e32 v0, v42, v0
	v_mov_b32_e32 v42, v0
	s_nop 1
	v_permlane16_swap_b32_e32 v42, v0
	s_nop 0
	v_add_f32_e32 v0, v0, v42
	v_mov_b32_e32 v42, v0
	s_nop 1
	v_permlane32_swap_b32_e32 v42, v0
	s_nop 0
	s_and_saveexec_b64 s[0:1], s[36:37]
	s_cbranch_execz .LBB0_349
	s_lshl_b32 s3, s2, 16
	v_readlane_b32 s14, v252, 17
	s_add_u32 s14, s14, s3
	v_readlane_b32 s3, v252, 18
	s_addc_u32 s15, s3, 0
	v_lshl_add_u64 v[44:45], v[158:159], 2, s[14:15]
	s_waitcnt lgkmcnt(0)
	v_add_f32_e32 v0, v0, v42
	global_atomic_add_f32 v[44:45], v0, off offset:576

; __device__ __forceinline__ unsigned cvt_pk_bf16(float lo, float hi) { f32x2 v = {lo, hi}; bf16x2_t b = __builtin_convertvector(v, bf16x2_t); return __builtin_bit_cast(unsigned, b); }
;     __device__ __forceinline__ void operator()(ACC_T, const Unit& u, int wr, int wc, int fr, int fq) const {
;     ...
;                 for (int m = 0; m < 4; ++m) { bf16_t* rowp = P + (size_t)(row0 + ai * HALF + m * 16) * PW + col0;
; #pragma unroll
;                     for (int bj = 0; bj < 2; ++bj) { const f32x4 v0 = acc[ai][bj][m][0] * sc, v1 = acc[ai][bj][m][1] * sc;
;                         u32x4 w; w.x = cvt_pk_bf16(v0[0], v0[1]); w.y = cvt_pk_bf16(v0[2], v0[3]); w.z = cvt_pk_bf16(v1[0], v1[1]); w.w = cvt_pk_bf16(v1[2], v1[3]);
;                         *(u32x4*)(rowp + bj * HALF) = w;
;                         if (u.pn == 8 || u.pn == 9) {
;                             float q = (v0[0] * v0[0] + v0[1] * v0[1]) + (v0[2] * v0[2] + v0[3] * v0[3]) + (v1[0] * v1[0] + v1[1] * v1[1]) + (v1[2] * v1[2] + v1[3] * v1[3]);
;                             q += __shfl_xor(q, 16); q += __shfl_xor(q, 32);
;                             if (fq == 0) __hip_atomic_fetch_add(kn2 + (size_t)((u.pn - 8) * 4 + bj * 2 + (wc >> 1)) * T + (row0 + ai * HALF + m * 16), q, __ATOMIC_RELAXED, __HIP_MEMORY_SCOPE_AGENT); } } }
.LBB0_350:
	s_waitcnt lgkmcnt(0)
	v_mov_b32_e32 v42, v130
	v_mov_b32_e32 v43, v130
	v_pk_mul_f32 v[40:41], v[42:43], v[40:41]
	v_pk_mul_f32 v[38:39], v[130:131], v[38:39]
	v_pk_mul_f32 v[36:37], v[42:43], v[36:37]
	v_pk_mul_f32 v[34:35], v[130:131], v[34:35]
	v_cvt_pk_bf16_f32 v44, v38, v39
	v_cvt_pk_bf16_f32 v45, v40, v41
	v_cvt_pk_bf16_f32 v46, v34, v35
	v_cvt_pk_bf16_f32 v47, v36, v37
	s_and_b64 vcc, exec, s[40:41]
	global_store_dwordx4 v[50:51], v[44:47], off offset:256
	s_cbranch_vccnz .LBB0_354
	v_mul_f32_e32 v0, v39, v39
	v_fmac_f32_e32 v0, v38, v38
	v_mul_f32_e32 v38, v41, v41
	v_fmac_f32_e32 v38, v40, v40
	v_mul_f32_e32 v35, v35, v35
	v_add_f32_e32 v0, v0, v38
	v_fmac_f32_e32 v35, v34, v34
	v_mul_f32_e32 v34, v37, v37
	v_add_f32_e32 v0, v0, v35
	v_fmac_f32_e32 v34, v36, v36
	v_and_b32_e32 v35, 64, v230
	v_add_f32_e32 v0, v34, v0
	v_mov_b32_e32 v34, v0
	s_nop 1
	v_permlane16_swap_b32_e32 v34, v0
	s_nop 0
	v_add_f32_e32 v0, v0, v34
	v_mov_b32_e32 v34, v0
	s_nop 1
	v_permlane32_swap_b32_e32 v34, v0
	s_nop 0
	s_and_saveexec_b64 s[0:1], s[36:37]
	s_cbranch_execz .LBB0_353
	s_lshl_b32 s3, s2, 16
	v_readlane_b32 s14, v252, 17
	s_add_u32 s14, s14, s3
	v_readlane_b32 s3, v252, 18
	v_ashrrev_i32_e32 v161, 31, v160
	s_addc_u32 s15, s3, 0
	v_lshl_add_u64 v[36:37], v[160:161], 2, s[14:15]
	s_waitcnt lgkmcnt(0)
	v_add_f32_e32 v0, v0, v34
	v_add_co_u32_e32 v34, vcc, 0x20000, v36
	s_nop 1
	v_addc_co_u32_e32 v35, vcc, 0, v37, vcc
	global_atomic_add_f32 v[34:35], v0, off

; __device__ __forceinline__ unsigned cvt_pk_bf16(float lo, float hi) { f32x2 v = {lo, hi}; bf16x2_t b = __builtin_convertvector(v, bf16x2_t); return __builtin_bit_cast(unsigned, b); }
;     __device__ __forceinline__ void operator()(ACC_T, const Unit& u, int wr, int wc, int fr, int fq) const {
;     ...
;                 for (int m = 0; m < 4; ++m) { bf16_t* rowp = P + (size_t)(row0 + ai * HALF + m * 16) * PW + col0;
; #pragma unroll
;                     for (int bj = 0; bj < 2; ++bj) { const f32x4 v0 = acc[ai][bj][m][0] * sc, v1 = acc[ai][bj][m][1] * sc;
;                         u32x4 w; w.x = cvt_pk_bf16(v0[0], v0[1]); w.y = cvt_pk_bf16(v0[2], v0[3]); w.z = cvt_pk_bf16(v1[0], v1[1]); w.w = cvt_pk_bf16(v1[2], v1[3]);
;                         *(u32x4*)(rowp + bj * HALF) = w;
;                         if (u.pn == 8 || u.pn == 9) {
;                             float q = (v0[0] * v0[0] + v0[1] * v0[1]) + (v0[2] * v0[2] + v0[3] * v0[3]) + (v1[0] * v1[0] + v1[1] * v1[1]) + (v1[2] * v1[2] + v1[3] * v1[3]);
;                             q += __shfl_xor(q, 16); q += __shfl_xor(q, 32);
;                             if (fq == 0) __hip_atomic_fetch_add(kn2 + (size_t)((u.pn - 8) * 4 + bj * 2 + (wc >> 1)) * T + (row0 + ai * HALF + m * 16), q, __ATOMIC_RELAXED, __HIP_MEMORY_SCOPE_AGENT); } } }
.LBB0_354:
	v_readlane_b32 s0, v251, 56
	v_readlane_b32 s1, v251, 57
	s_waitcnt lgkmcnt(0)
	v_add_u32_e32 v34, 0xa0, v158
	v_pk_mul_f32 v[32:33], v[42:43], v[32:33]
	v_mov_b64_e32 v[36:37], s[0:1]
	s_movk_i32 s0, 0x1c00
	v_mad_i64_i32 v[36:37], s[0:1], v34, s0, v[36:37]
	v_pk_mul_f32 v[30:31], v[130:131], v[30:31]
	v_pk_mul_f32 v[28:29], v[42:43], v[28:29]
	v_pk_mul_f32 v[26:27], v[130:131], v[26:27]
	v_lshl_add_u64 v[36:37], v[132:133], 1, v[36:37]
	v_cvt_pk_bf16_f32 v38, v30, v31
	v_cvt_pk_bf16_f32 v39, v32, v33
	v_cvt_pk_bf16_f32 v40, v26, v27
	v_cvt_pk_bf16_f32 v41, v28, v29
	s_and_b64 vcc, exec, s[40:41]
	global_store_dwordx4 v[36:37], v[38:41], off
	s_cbranch_vccnz .LBB0_358
	v_mul_f32_e32 v0, v31, v31
	v_fmac_f32_e32 v0, v30, v30
	v_mul_f32_e32 v30, v33, v33
	v_fmac_f32_e32 v30, v32, v32
	v_mul_f32_e32 v27, v27, v27
	v_add_f32_e32 v0, v0, v30
	v_fmac_f32_e32 v27, v26, v26
	v_mul_f32_e32 v26, v29, v29
	v_add_f32_e32 v0, v0, v27
	v_fmac_f32_e32 v26, v28, v28
	v_and_b32_e32 v27, 64, v230
	v_add_f32_e32 v0, v26, v0
	v_mov_b32_e32 v26, v0
	s_nop 1
	v_permlane16_swap_b32_e32 v26, v0
	s_nop 0
	v_add_f32_e32 v0, v0, v26
	v_mov_b32_e32 v26, v0
	s_nop 1
	v_permlane32_swap_b32_e32 v26, v0
	s_nop 0
	s_and_saveexec_b64 s[0:1], s[36:37]
	s_cbranch_execz .LBB0_357
	s_lshl_b32 s3, s2, 16
	v_readlane_b32 s14, v252, 17
	s_add_u32 s14, s14, s3
	v_readlane_b32 s3, v252, 18
	s_addc_u32 s15, s3, 0
	v_lshl_add_u64 v[28:29], v[158:159], 2, s[14:15]
	s_waitcnt lgkmcnt(0)
	v_add_f32_e32 v0, v0, v26
	global_atomic_add_f32 v[28:29], v0, off offset:640

; __device__ __forceinline__ unsigned cvt_pk_bf16(float lo, float hi) { f32x2 v = {lo, hi}; bf16x2_t b = __builtin_convertvector(v, bf16x2_t); return __builtin_bit_cast(unsigned, b); }
;     __device__ __forceinline__ void operator()(ACC_T, const Unit& u, int wr, int wc, int fr, int fq) const {
;     ...
;                 for (int m = 0; m < 4; ++m) { bf16_t* rowp = P + (size_t)(row0 + ai * HALF + m * 16) * PW + col0;
; #pragma unroll
;                     for (int bj = 0; bj < 2; ++bj) { const f32x4 v0 = acc[ai][bj][m][0] * sc, v1 = acc[ai][bj][m][1] * sc;
;                         u32x4 w; w.x = cvt_pk_bf16(v0[0], v0[1]); w.y = cvt_pk_bf16(v0[2], v0[3]); w.z = cvt_pk_bf16(v1[0], v1[1]); w.w = cvt_pk_bf16(v1[2], v1[3]);
;                         *(u32x4*)(rowp + bj * HALF) = w;
;                         if (u.pn == 8 || u.pn == 9) {
;                             float q = (v0[0] * v0[0] + v0[1] * v0[1]) + (v0[2] * v0[2] + v0[3] * v0[3]) + (v1[0] * v1[0] + v1[1] * v1[1]) + (v1[2] * v1[2] + v1[3] * v1[3]);
;                             q += __shfl_xor(q, 16); q += __shfl_xor(q, 32);
;                             if (fq == 0) __hip_atomic_fetch_add(kn2 + (size_t)((u.pn - 8) * 4 + bj * 2 + (wc >> 1)) * T + (row0 + ai * HALF + m * 16), q, __ATOMIC_RELAXED, __HIP_MEMORY_SCOPE_AGENT); } } }
.LBB0_358:
	s_waitcnt lgkmcnt(0)
	v_mov_b32_e32 v26, v130
	v_mov_b32_e32 v27, v130
	v_pk_mul_f32 v[24:25], v[26:27], v[24:25]
	v_pk_mul_f32 v[22:23], v[130:131], v[22:23]
	v_pk_mul_f32 v[20:21], v[26:27], v[20:21]
	v_pk_mul_f32 v[18:19], v[130:131], v[18:19]
	v_cvt_pk_bf16_f32 v28, v22, v23
	v_cvt_pk_bf16_f32 v29, v24, v25
	v_cvt_pk_bf16_f32 v30, v18, v19
	v_cvt_pk_bf16_f32 v31, v20, v21
	s_and_b64 vcc, exec, s[40:41]
	global_store_dwordx4 v[36:37], v[28:31], off offset:256
	s_cbranch_vccnz .LBB0_362
	v_mul_f32_e32 v0, v23, v23
	v_fmac_f32_e32 v0, v22, v22
	v_mul_f32_e32 v22, v25, v25
	v_fmac_f32_e32 v22, v24, v24
	v_mul_f32_e32 v19, v19, v19
	v_add_f32_e32 v0, v0, v22
	v_fmac_f32_e32 v19, v18, v18
	v_mul_f32_e32 v18, v21, v21
	v_add_f32_e32 v0, v0, v19
	v_fmac_f32_e32 v18, v20, v20
	v_and_b32_e32 v19, 64, v230
	v_add_f32_e32 v0, v18, v0
	v_mov_b32_e32 v18, v0
	s_nop 1
	v_permlane16_swap_b32_e32 v18, v0
	s_nop 0
	v_add_f32_e32 v0, v0, v18
	v_mov_b32_e32 v18, v0
	s_nop 1
	v_permlane32_swap_b32_e32 v18, v0
	s_nop 0
	s_and_saveexec_b64 s[0:1], s[36:37]
	s_cbranch_execz .LBB0_361
	s_lshl_b32 s3, s2, 16
	v_readlane_b32 s14, v252, 17
	s_add_u32 s14, s14, s3
	v_readlane_b32 s3, v252, 18
	v_ashrrev_i32_e32 v35, 31, v34
	s_addc_u32 s15, s3, 0
	v_lshl_add_u64 v[20:21], v[34:35], 2, s[14:15]
	s_waitcnt lgkmcnt(0)
	v_add_f32_e32 v0, v0, v18
	v_add_co_u32_e32 v18, vcc, 0x20000, v20
	s_nop 1
	v_addc_co_u32_e32 v19, vcc, 0, v21, vcc
	global_atomic_add_f32 v[18:19], v0, off

; __device__ __forceinline__ unsigned cvt_pk_bf16(float lo, float hi) { f32x2 v = {lo, hi}; bf16x2_t b = __builtin_convertvector(v, bf16x2_t); return __builtin_bit_cast(unsigned, b); }
;     __device__ __forceinline__ void operator()(ACC_T, const Unit& u, int wr, int wc, int fr, int fq) const {
;     ...
;                 for (int m = 0; m < 4; ++m) { bf16_t* rowp = P + (size_t)(row0 + ai * HALF + m * 16) * PW + col0;
; #pragma unroll
;                     for (int bj = 0; bj < 2; ++bj) { const f32x4 v0 = acc[ai][bj][m][0] * sc, v1 = acc[ai][bj][m][1] * sc;
;                         u32x4 w; w.x = cvt_pk_bf16(v0[0], v0[1]); w.y = cvt_pk_bf16(v0[2], v0[3]); w.z = cvt_pk_bf16(v1[0], v1[1]); w.w = cvt_pk_bf16(v1[2], v1[3]);
;                         *(u32x4*)(rowp + bj * HALF) = w;
;                         if (u.pn == 8 || u.pn == 9) {
;                             float q = (v0[0] * v0[0] + v0[1] * v0[1]) + (v0[2] * v0[2] + v0[3] * v0[3]) + (v1[0] * v1[0] + v1[1] * v1[1]) + (v1[2] * v1[2] + v1[3] * v1[3]);
;                             q += __shfl_xor(q, 16); q += __shfl_xor(q, 32);
;                             if (fq == 0) __hip_atomic_fetch_add(kn2 + (size_t)((u.pn - 8) * 4 + bj * 2 + (wc >> 1)) * T + (row0 + ai * HALF + m * 16), q, __ATOMIC_RELAXED, __HIP_MEMORY_SCOPE_AGENT); } } }
.LBB0_362:
	v_readlane_b32 s0, v251, 56
	v_readlane_b32 s1, v251, 57
	s_waitcnt lgkmcnt(0)
	v_add_u32_e32 v18, 0xb0, v158
	v_pk_mul_f32 v[16:17], v[26:27], v[16:17]
	v_mov_b64_e32 v[20:21], s[0:1]
	s_movk_i32 s0, 0x1c00
	v_mad_i64_i32 v[20:21], s[0:1], v18, s0, v[20:21]
	v_pk_mul_f32 v[14:15], v[130:131], v[14:15]
	v_pk_mul_f32 v[12:13], v[26:27], v[12:13]
	v_pk_mul_f32 v[10:11], v[130:131], v[10:11]
	v_lshl_add_u64 v[20:21], v[132:133], 1, v[20:21]
	v_cvt_pk_bf16_f32 v22, v14, v15
	v_cvt_pk_bf16_f32 v23, v16, v17
	v_cvt_pk_bf16_f32 v24, v10, v11
	v_cvt_pk_bf16_f32 v25, v12, v13
	s_and_b64 vcc, exec, s[40:41]
	global_store_dwordx4 v[20:21], v[22:25], off
	s_cbranch_vccnz .LBB0_366
	v_mul_f32_e32 v0, v15, v15
	v_fmac_f32_e32 v0, v14, v14
	v_mul_f32_e32 v14, v17, v17
	v_fmac_f32_e32 v14, v16, v16
	v_mul_f32_e32 v11, v11, v11
	v_add_f32_e32 v0, v0, v14
	v_fmac_f32_e32 v11, v10, v10
	v_mul_f32_e32 v10, v13, v13
	v_add_f32_e32 v0, v0, v11
	v_fmac_f32_e32 v10, v12, v12
	v_and_b32_e32 v11, 64, v230
	v_add_f32_e32 v0, v10, v0
	v_mov_b32_e32 v10, v0
	s_nop 1
	v_permlane16_swap_b32_e32 v10, v0
	s_nop 0
	v_add_f32_e32 v0, v0, v10
	v_mov_b32_e32 v10, v0
	s_nop 1
	v_permlane32_swap_b32_e32 v10, v0
	s_nop 0
	s_and_saveexec_b64 s[0:1], s[36:37]
	s_cbranch_execz .LBB0_365
	s_lshl_b32 s3, s2, 16
	v_readlane_b32 s14, v252, 17
	s_add_u32 s14, s14, s3
	v_readlane_b32 s3, v252, 18
	s_addc_u32 s15, s3, 0
	v_lshl_add_u64 v[12:13], v[158:159], 2, s[14:15]
	s_waitcnt lgkmcnt(0)
	v_add_f32_e32 v0, v0, v10
	global_atomic_add_f32 v[12:13], v0, off offset:704

; __device__ __forceinline__ unsigned cvt_pk_bf16(float lo, float hi) { f32x2 v = {lo, hi}; bf16x2_t b = __builtin_convertvector(v, bf16x2_t); return __builtin_bit_cast(unsigned, b); }
;     __device__ __forceinline__ void operator()(ACC_T, const Unit& u, int wr, int wc, int fr, int fq) const {
;     ...
;                 for (int m = 0; m < 4; ++m) { bf16_t* rowp = P + (size_t)(row0 + ai * HALF + m * 16) * PW + col0;
; #pragma unroll
;                     for (int bj = 0; bj < 2; ++bj) { const f32x4 v0 = acc[ai][bj][m][0] * sc, v1 = acc[ai][bj][m][1] * sc;
;                         u32x4 w; w.x = cvt_pk_bf16(v0[0], v0[1]); w.y = cvt_pk_bf16(v0[2], v0[3]); w.z = cvt_pk_bf16(v1[0], v1[1]); w.w = cvt_pk_bf16(v1[2], v1[3]);
;                         *(u32x4*)(rowp + bj * HALF) = w;
;                         if (u.pn == 8 || u.pn == 9) {
;                             float q = (v0[0] * v0[0] + v0[1] * v0[1]) + (v0[2] * v0[2] + v0[3] * v0[3]) + (v1[0] * v1[0] + v1[1] * v1[1]) + (v1[2] * v1[2] + v1[3] * v1[3]);
;                             q += __shfl_xor(q, 16); q += __shfl_xor(q, 32);
;                             if (fq == 0) __hip_atomic_fetch_add(kn2 + (size_t)((u.pn - 8) * 4 + bj * 2 + (wc >> 1)) * T + (row0 + ai * HALF + m * 16), q, __ATOMIC_RELAXED, __HIP_MEMORY_SCOPE_AGENT); } } }
.LBB0_366:
	s_waitcnt lgkmcnt(0)
	v_mov_b32_e32 v10, v130
	v_mov_b32_e32 v11, v130
	v_pk_mul_f32 v[8:9], v[10:11], v[8:9]
	v_pk_mul_f32 v[6:7], v[130:131], v[6:7]
	v_pk_mul_f32 v[4:5], v[10:11], v[4:5]
	v_pk_mul_f32 v[2:3], v[130:131], v[2:3]
	v_cvt_pk_bf16_f32 v10, v6, v7
	v_cvt_pk_bf16_f32 v11, v8, v9
	v_cvt_pk_bf16_f32 v12, v2, v3
	v_cvt_pk_bf16_f32 v13, v4, v5
	s_and_b64 vcc, exec, s[40:41]
	global_store_dwordx4 v[20:21], v[10:13], off offset:256
	s_cbranch_vccnz .LBB0_370
	v_mul_f32_e32 v0, v7, v7
	v_fmac_f32_e32 v0, v6, v6
	v_mul_f32_e32 v6, v9, v9
	v_fmac_f32_e32 v6, v8, v8
	v_mul_f32_e32 v3, v3, v3
	v_add_f32_e32 v0, v0, v6
	v_fmac_f32_e32 v3, v2, v2
	v_mul_f32_e32 v2, v5, v5
	v_add_f32_e32 v0, v0, v3
	v_fmac_f32_e32 v2, v4, v4
	v_and_b32_e32 v3, 64, v230
	v_add_f32_e32 v0, v2, v0
	v_mov_b32_e32 v2, v0
	s_nop 1
	v_permlane16_swap_b32_e32 v2, v0
	s_nop 0
	v_add_f32_e32 v0, v0, v2
	v_mov_b32_e32 v2, v0
	s_nop 1
	v_permlane32_swap_b32_e32 v2, v0
	s_nop 0
	s_and_saveexec_b64 s[0:1], s[36:37]
	s_cbranch_execz .LBB0_369
	s_lshl_b32 s2, s2, 16
	v_readlane_b32 s3, v252, 17
	s_add_u32 s2, s3, s2
	v_readlane_b32 s3, v252, 18
	v_ashrrev_i32_e32 v19, 31, v18
	s_addc_u32 s3, s3, 0
	v_lshl_add_u64 v[4:5], v[18:19], 2, s[2:3]
	s_waitcnt lgkmcnt(0)
	v_add_f32_e32 v0, v0, v2
	v_add_co_u32_e32 v2, vcc, 0x20000, v4
	s_nop 1
	v_addc_co_u32_e32 v3, vcc, 0, v5, vcc
	global_atomic_add_f32 v[2:3], v0, off
